# prep-phase queue: each workgroup's first ticket is its blockIdx (no 256-way same-address atomic at kernel start); later tickets atomic+256
# speedup vs baseline: 1.0063x; 1.0029x over previous
_Z11mega_kernel6Params:
	s_load_dwordx8 s[4:11], s[0:1], 0xc0
	s_load_dword s3, s[0:1], 0xf8
	s_load_dwordx4 s[28:31], s[0:1], 0xe0
	s_load_dwordx2 s[96:97], s[0:1], 0xf0
	v_and_b32_e32 v188, 0x3ff, v0
	v_cmp_gt_u32_e32 vcc, 4, v188
	s_waitcnt lgkmcnt(0)
	s_mov_b32 s100, 1
	v_writelane_b32 v254, s100, 4
	v_writelane_b32 v253, s4, 0
	s_nop 1
	v_writelane_b32 v253, s5, 1
	v_writelane_b32 v253, s6, 2
	v_writelane_b32 v253, s7, 3
	v_writelane_b32 v253, s8, 4
	v_writelane_b32 v253, s9, 5
	v_writelane_b32 v253, s10, 6
	v_writelane_b32 v253, s11, 7
	s_add_u32 s4, s0, 0xf0
	v_writelane_b32 v253, s3, 8
	s_addc_u32 s5, s1, 0
	s_and_saveexec_b64 s[6:7], vcc
	v_lshl_add_u32 v1, v188, 2, 0
	v_add_u32_e32 v1, 0x24000, v1
	v_mov_b32_e32 v2, 0
	ds_write_b32 v1, v2
	s_or_b64 exec, exec, s[6:7]
	s_waitcnt lgkmcnt(0)
	s_barrier
	s_add_u32 s34, s30, 0xf79c000
	s_getreg_b32 s3, hwreg(HW_REG_XCC_ID, 0, 4)
	s_addc_u32 s35, s31, 0
	s_and_b32 s12, s3, 15
	v_cmp_eq_u32_e64 s[62:63], 0, v188
	s_and_saveexec_b64 s[6:7], s[62:63]
	s_cbranch_execz .LBB0_5
	s_mov_b64 s[8:9], exec
	v_mbcnt_lo_u32_b32 v1, s8, 0
	v_mbcnt_hi_u32_b32 v1, s9, v1
	v_cmp_eq_u32_e32 vcc, 0, v1
	s_and_b64 s[10:11], exec, vcc
	s_mov_b64 exec, s[10:11]
	s_cbranch_execz .LBB0_5
	s_lshl_b32 s3, s12, 8
	s_bcnt1_i32_b64 s8, s[8:9]
	v_mov_b32_e32 v1, s3
	v_mov_b32_e32 v2, s8
	global_atomic_add v1, v2, s[34:35] offset:1024

.LBB0_21:
	s_waitcnt lgkmcnt(0)
	s_barrier
	v_readlane_b32 s100, v254, 4
	s_nop 3
	s_cmp_eq_u32 s100, 0
	s_cbranch_scc1 .Lp_dyn
	s_mov_b32 s101, 0
	v_writelane_b32 v254, s101, 4
	s_and_saveexec_b64 s[6:7], s[62:63]
	v_mov_b32_e32 v1, s3
	v_mov_b32_e32 v0, s2
	s_brev_b32 s48, 18
	s_movk_i32 s40, 0x1f8
	s_mov_b32 s49, 0x8000
	ds_write_b32 v1, v0
	s_branch .LBB0_25
.Lp_dyn:
	s_and_saveexec_b64 s[6:7], s[62:63]
	s_cbranch_execz .LBB0_25
	s_mov_b64 s[10:11], exec
	v_mbcnt_lo_u32_b32 v0, s10, 0
	v_mbcnt_hi_u32_b32 v0, s11, v0
	v_cmp_eq_u32_e32 vcc, 0, v0
	s_and_saveexec_b64 s[8:9], vcc
	s_cbranch_execz .LBB0_24
	s_bcnt1_i32_b64 s10, s[10:11]
	v_mov_b32_e32 v1, s10
	global_atomic_add v1, v61, v1, s[52:53] sc0
.LBB0_24:
	s_or_b64 exec, exec, s[8:9]
	s_waitcnt vmcnt(0)
	v_readfirstlane_b32 s8, v1
	v_mov_b32_e32 v1, s3
	s_brev_b32 s48, 18
	s_addk_i32 s8, 0x100
	v_add_u32_e32 v0, s8, v0
	s_movk_i32 s40, 0x1f8
	s_mov_b32 s49, 0x8000
	ds_write_b32 v1, v0
